# attention: sub-LN wave reduction by DPP row ops + permlane16_swap instead of 80 bpermutes; phase set-up loads issued together and its four reductions advanced in lock step
# speedup vs baseline: 1.0234x; 1.0046x over previous
; __global__ void __launch_bounds__(NWAVES * 64, 2) hybrid_fwd(Args args) {
;     ...
;             const float lam_init = 0.8f - 0.6f * expf(-0.3f * (float)ll);
;             float a = args.in[z + 6][ll * 64 + lane] * args.in[z + 7][ll * 64 + lane], b2 = args.in[z + 8][ll * 64 + lane] * args.in[z + 9][ll * 64 + lane];
;             a = wave_sum(a); b2 = wave_sum(b2);
;             const float lam = expf(a) - expf(b2) + lam_init;
;             float gqm = fabsf(args.in[z + 4][ll * 64 + lane]), gkm = fabsf(args.in[z + 5][ll * 64 + lane]);
; #pragma unroll
;             for (int o = 1; o < 64; o <<= 1) { gqm = fmaxf(gqm, __shfl_xor(gqm, o)); gkm = fmaxf(gkm, __shfl_xor(gkm, o)); }
;             const float gqk = gqm * gkm;
.LBB0_293:
	v_readlane_b32 s6, v254, 1
	s_cmp_le_i32 s6, s3
	s_cselect_b64 s[0:1], -1, 0
	v_readlane_b32 s7, v254, 2
	s_and_b64 s[0:1], s[0:1], s[10:11]
	s_add_i32 s24, s27, 3
	s_cmp_lt_i32 s24, s7
	s_cselect_b64 s[78:79], -1, 0
	s_andn2_b64 vcc, exec, s[0:1]
	s_cbranch_vccnz .LBB0_436
	s_mov_b32 s3, s26
	s_mov_b32 s0, s15
	s_ashr_i32 s1, s0, 31
	s_lshl_b64 s[0:1], s[0:1], 3
	s_add_u32 s0, s84, s0
	s_addc_u32 s1, s85, s1
	s_load_dwordx8 s[48:55], s[0:1], 0x20
	s_load_dwordx4 s[8:11], s[0:1], 0x40
	s_waitcnt vmcnt(0)
	v_lshl_or_b32 v0, s3, 6, v177
	s_waitcnt lgkmcnt(0)
	v_ashrrev_i32_e32 v1, 31, v0
	v_lshlrev_b64 v[4:5], 2, v[0:1]
	s_waitcnt lgkmcnt(0)
	v_lshl_add_u64 v[10:11], s[52:53], 0, v[4:5]
	global_load_dword v2, v[10:11], off
	v_lshl_add_u64 v[10:11], s[54:55], 0, v[4:5]
	global_load_dword v3, v[10:11], off
	v_lshl_add_u64 v[10:11], s[8:9], 0, v[4:5]
	global_load_dword v7, v[10:11], off
	v_lshl_add_u64 v[10:11], s[10:11], 0, v[4:5]
	global_load_dword v1, v[10:11], off
	v_lshl_add_u64 v[10:11], s[48:49], 0, v[4:5]
	global_load_dword v12, v[10:11], off
	v_lshl_add_u64 v[10:11], s[50:51], 0, v[4:5]
	global_load_dword v13, v[10:11], off
	v_xor_b32_e32 v18, 1, v190
	v_cmp_lt_i32_e32 vcc, v18, v192
	s_nop 1
	v_cndmask_b32_e32 v18, v190, v18, vcc
	v_lshlrev_b32_e32 v135, 2, v18
	v_xor_b32_e32 v18, 2, v190
	v_cmp_lt_i32_e32 vcc, v18, v192
	s_nop 1
	v_cndmask_b32_e32 v18, v190, v18, vcc
	v_lshlrev_b32_e32 v142, 2, v18
	v_xor_b32_e32 v18, 4, v190
	v_cmp_lt_i32_e32 vcc, v18, v192
	s_nop 1
	v_cndmask_b32_e32 v18, v190, v18, vcc
	v_lshlrev_b32_e32 v143, 2, v18
	v_xor_b32_e32 v18, 8, v190
	v_cmp_lt_i32_e32 vcc, v18, v192
	s_nop 1
	v_cndmask_b32_e32 v18, v190, v18, vcc
	v_lshlrev_b32_e32 v160, 2, v18
	v_cmp_lt_i32_e32 vcc, v191, v192
	s_nop 1
	v_cndmask_b32_e32 v18, v190, v191, vcc
	v_lshlrev_b32_e32 v161, 2, v18
	v_cmp_lt_i32_e32 vcc, v193, v192
	s_nop 1
	v_cndmask_b32_e32 v18, v190, v193, vcc
	v_lshlrev_b32_e32 v162, 2, v18
	v_readlane_b32 s6, v254, 61
	v_readlane_b32 s7, v254, 62
	v_writelane_b32 v255, s24, 46
	s_waitcnt vmcnt(0)
	v_mul_f32_e32 v6, v2, v3
	v_mul_f32_e32 v8, v7, v1
	v_and_b32_e32 v14, 0x7fffffff, v12
	v_and_b32_e32 v15, 0x7fffffff, v13
	ds_bpermute_b32 v0, v135, v6
	ds_bpermute_b32 v9, v135, v8
	ds_bpermute_b32 v16, v135, v14
	ds_bpermute_b32 v17, v135, v15
	v_max_f32_e64 v12, |v12|, |v12|
	v_max_f32_e64 v13, |v13|, |v13|
	s_waitcnt lgkmcnt(0)
	v_fmac_f32_e32 v0, v2, v3
	v_fmac_f32_e32 v9, v7, v1
	v_max_f32_e32 v16, v16, v16
	v_max_f32_e32 v12, v12, v16
	v_max_f32_e32 v17, v17, v17
	v_max_f32_e32 v13, v13, v17
	ds_bpermute_b32 v2, v142, v0
	ds_bpermute_b32 v3, v142, v9
	ds_bpermute_b32 v16, v142, v12
	ds_bpermute_b32 v17, v142, v13
	s_waitcnt lgkmcnt(0)
	v_add_f32_e32 v0, v0, v2
	v_add_f32_e32 v9, v9, v3
	v_max_f32_e32 v16, v16, v16
	v_max_f32_e32 v12, v12, v16
	v_max_f32_e32 v17, v17, v17
	v_max_f32_e32 v13, v13, v17
	ds_bpermute_b32 v2, v143, v0
	ds_bpermute_b32 v3, v143, v9
	ds_bpermute_b32 v16, v143, v12
	ds_bpermute_b32 v17, v143, v13
	s_waitcnt lgkmcnt(0)
	v_add_f32_e32 v0, v0, v2
	v_add_f32_e32 v9, v9, v3
	v_max_f32_e32 v16, v16, v16
	v_max_f32_e32 v12, v12, v16
	v_max_f32_e32 v17, v17, v17
	v_max_f32_e32 v13, v13, v17
	ds_bpermute_b32 v2, v160, v0
	ds_bpermute_b32 v3, v160, v9
	ds_bpermute_b32 v16, v160, v12
	ds_bpermute_b32 v17, v160, v13
	s_waitcnt lgkmcnt(0)
	v_add_f32_e32 v0, v0, v2
	v_add_f32_e32 v9, v9, v3
	v_max_f32_e32 v16, v16, v16
	v_max_f32_e32 v12, v12, v16
	v_max_f32_e32 v17, v17, v17
	v_max_f32_e32 v13, v13, v17
	ds_bpermute_b32 v2, v161, v0
	ds_bpermute_b32 v3, v161, v9
	ds_bpermute_b32 v16, v161, v12
	ds_bpermute_b32 v17, v161, v13
	s_waitcnt lgkmcnt(0)
	v_add_f32_e32 v0, v0, v2
	v_add_f32_e32 v9, v9, v3
	v_max_f32_e32 v16, v16, v16
	v_max_f32_e32 v12, v12, v16
	v_max_f32_e32 v17, v17, v17
	v_max_f32_e32 v13, v13, v17
	v_mov_b32_e32 v1, v9
	v_mov_b32_e32 v4, v12
	v_mov_b32_e32 v6, v13
	ds_bpermute_b32 v3, v162, v0
	ds_bpermute_b32 v2, v162, v1
	ds_bpermute_b32 v5, v162, v4
	ds_bpermute_b32 v7, v162, v6
	s_waitcnt lgkmcnt(0)
	s_andn2_b64 vcc, exec, s[6:7]
	s_cbranch_vccnz .LBB0_382
	v_cvt_f32_i32_e32 v8, s3
	s_mov_b32 s8, 0x3fb8aa3b
	v_add_f32_e32 v0, v0, v3
	v_mul_f32_e32 v3, 0x3fb8aa3b, v0
	v_mul_f32_e32 v8, 0xbe99999a, v8
	v_mul_f32_e32 v9, 0x3fb8aa3b, v8
	v_fma_f32 v10, v8, s8, -v9
	v_rndne_f32_e32 v11, v9
	v_fmac_f32_e32 v10, 0x32a5705f, v8
	v_sub_f32_e32 v9, v9, v11
	v_add_f32_e32 v9, v9, v10
	v_exp_f32_e32 v9, v9
	v_cvt_i32_f32_e32 v10, v11
	v_rndne_f32_e32 v11, v3
	s_mov_b32 s9, 0xc2ce8ed0
	v_cmp_ngt_f32_e32 vcc, s9, v8
	v_ldexp_f32 v9, v9, v10
	v_fma_f32 v10, v0, s8, -v3
	v_fmac_f32_e32 v10, 0x32a5705f, v0
	v_sub_f32_e32 v3, v3, v11
	v_add_f32_e32 v3, v3, v10
	v_exp_f32_e32 v3, v3
	v_cvt_i32_f32_e32 v10, v11
	s_mov_b32 s10, 0x42b17218
	v_add_f32_e32 v1, v1, v2
	v_cndmask_b32_e32 v9, 0, v9, vcc
	v_cmp_nlt_f32_e32 vcc, s10, v8
	v_ldexp_f32 v2, v3, v10
	v_mul_f32_e32 v3, 0x3fb8aa3b, v1
	s_load_dwordx2 s[16:17], s[0:1], 0x88
	v_cndmask_b32_e32 v8, v195, v9, vcc
	v_fma_f32 v9, v1, s8, -v3
	v_rndne_f32_e32 v10, v3
	v_fmac_f32_e32 v9, 0x32a5705f, v1
	v_sub_f32_e32 v3, v3, v10
	v_add_f32_e32 v3, v3, v9
	v_exp_f32_e32 v3, v3
	v_cvt_i32_f32_e32 v9, v10
	s_waitcnt lgkmcnt(0)
	s_add_u32 s42, s16, 0x20200000
	v_cmp_ngt_f32_e32 vcc, s9, v0
	s_addc_u32 s43, s17, 0
	s_add_u32 s14, s16, 0x1a200000
	v_cndmask_b32_e32 v2, 0, v2, vcc
	v_cmp_nlt_f32_e32 vcc, s10, v0
	s_load_dwordx2 s[6:7], s[0:1], 0x18
	s_nop 0
	s_load_dwordx2 s[0:1], s[0:1], 0x50
	v_cndmask_b32_e32 v0, v195, v2, vcc
	v_ldexp_f32 v2, v3, v9
	v_cmp_ngt_f32_e32 vcc, s9, v1
	s_addc_u32 s46, s17, 0
	s_add_u32 s48, s16, 0x80000
	v_cndmask_b32_e32 v2, 0, v2, vcc
	v_cmp_nlt_f32_e32 vcc, s10, v1
	v_writelane_b32 v255, s16, 47
	s_addc_u32 s49, s17, 0
	v_cndmask_b32_e32 v1, v195, v2, vcc
	v_sub_f32_e32 v0, v0, v1
	v_mov_b32_e32 v1, 0x3f4ccccd
	s_lshl_b32 s8, s3, 7
	v_fmamk_f32 v1, v8, 0xbf19999a, v1
	s_ashr_i32 s9, s8, 31
	v_add_f32_e32 v163, v1, v0
	v_max_f32_e32 v0, v7, v7
	v_max_f32_e32 v2, v6, v6
	s_lshl_b64 s[8:9], s[8:9], 2
	v_max_f32_e32 v0, v2, v0
	v_max_f32_e32 v2, v5, v5
	v_max_f32_e32 v3, v4, v4
	s_waitcnt lgkmcnt(0)
	s_add_u32 s50, s0, s8
	v_max_f32_e32 v2, v3, v2
	s_mul_hi_i32 s10, s3, 0x3000
	s_mulk_i32 s3, 0x3000
	s_addc_u32 s51, s1, s9
	v_mul_f32_e32 v0, v0, v2
	s_add_u32 s52, s6, s3
	v_writelane_b32 v255, s17, 48
	v_mul_f32_e32 v164, 0x413ccccd, v0
	v_sub_f32_e32 v165, 1.0, v1
	s_addc_u32 s53, s7, s10
	v_readlane_b32 s47, v254, 0
	s_mov_b64 s[62:63], s[78:79]
	s_branch .LBB0_297

; template <bool FIXED> __device__ __forceinline__ void attn_unit(int b, int h, int qb, const bf16* __restrict__ P, bf16* __restrict__ MIX, const float* __restrict__ BT, const float* __restrict__ subg, ...
;     ...
;   if (m == 0) {
;     bf16* Ow = MIX + (rowbase + qw0) * DMODEL + h * 128 + r32;
;     float gsub[4];
; #pragma unroll
;     for (int d0 = 0; d0 < 4; ++d0) gsub[d0] = subg[d0 * 32 + r32] * post;
; #pragma unroll
;     for (int r = 0; r < 16; ++r) { float y[4]; float ss = 0.f;
; #pragma unroll
;       for (int d0 = 0; d0 < 4; ++d0) { y[d0] = o[d0][r] * rli[r] - xch[(d0 * 16 + r) * 64]; ss += y[d0] * y[d0]; }
.Lmy_nopf_a:
	ds_read2st64_b32 v[88:89], v72 offset1:1
	ds_read2st64_b32 v[90:91], v72 offset0:2 offset1:3
	ds_read2st64_b32 v[92:93], v72 offset0:4 offset1:5
	ds_read2st64_b32 v[94:95], v72 offset0:6 offset1:7
	ds_read2st64_b32 v[96:97], v72 offset0:8 offset1:9
	ds_read2st64_b32 v[98:99], v72 offset0:10 offset1:11
	ds_read2st64_b32 v[100:101], v72 offset0:12 offset1:13
	ds_read2st64_b32 v[102:103], v72 offset0:14 offset1:15
	ds_read2st64_b32 v[104:105], v72 offset0:16 offset1:17
	ds_read2st64_b32 v[106:107], v72 offset0:18 offset1:19
	ds_read2st64_b32 v[108:109], v72 offset0:20 offset1:21
	ds_read2st64_b32 v[110:111], v72 offset0:22 offset1:23
	ds_read2st64_b32 v[112:113], v72 offset0:24 offset1:25
	ds_read2st64_b32 v[114:115], v72 offset0:26 offset1:27
	ds_read2st64_b32 v[116:117], v72 offset0:28 offset1:29
	ds_read2st64_b32 v[118:119], v72 offset0:30 offset1:31
	ds_read2st64_b32 v[120:121], v72 offset0:32 offset1:33
	ds_read2st64_b32 v[122:123], v72 offset0:34 offset1:35
	ds_read2st64_b32 v[124:125], v72 offset0:36 offset1:37
	ds_read2st64_b32 v[126:127], v72 offset0:38 offset1:39
	ds_read2st64_b32 v[198:199], v72 offset0:40 offset1:41
	ds_read2st64_b32 v[200:201], v72 offset0:42 offset1:43
	ds_read2st64_b32 v[202:203], v72 offset0:44 offset1:45
	ds_read2st64_b32 v[204:205], v72 offset0:46 offset1:47
	ds_read2st64_b32 v[206:207], v72 offset0:48 offset1:49
	ds_read2st64_b32 v[208:209], v72 offset0:50 offset1:51
	ds_read2st64_b32 v[210:211], v72 offset0:52 offset1:53
	ds_read2st64_b32 v[212:213], v72 offset0:54 offset1:55
	ds_read2st64_b32 v[214:215], v72 offset0:56 offset1:57
	ds_read2st64_b32 v[216:217], v72 offset0:58 offset1:59
	ds_read2st64_b32 v[218:219], v72 offset0:60 offset1:61
	ds_read2st64_b32 v[220:221], v72 offset0:62 offset1:63
	s_lshl_b64 s[0:1], s[22:23], 12
	s_add_u32 s0, s68, s0
	s_addc_u32 s1, s69, s1
	v_lshlrev_b32_e32 v144, 1, v134
	v_lshl_add_u64 v[86:87], s[0:1], 0, v[144:145]
	v_lshlrev_b32_e32 v144, 14, v167
	v_lshl_add_u64 v[86:87], v[86:87], 0, v[144:145]
	s_waitcnt lgkmcnt(15)
	v_fma_f32 v0, v0, v64, -v88
	v_fma_f32 v1, v1, v85, -v89
	v_fma_f32 v2, v2, v84, -v90
	v_fma_f32 v3, v3, v83, -v91
	v_fma_f32 v4, v4, v82, -v92
	v_fma_f32 v5, v5, v81, -v93
	v_fma_f32 v6, v6, v80, -v94
	v_fma_f32 v7, v7, v79, -v95
	v_fma_f32 v8, v8, v78, -v96
	v_fma_f32 v9, v9, v77, -v97
	v_fma_f32 v10, v10, v76, -v98
	v_fma_f32 v11, v11, v75, -v99
	v_fma_f32 v12, v12, v74, -v100
	v_fma_f32 v13, v13, v73, -v101
	v_fma_f32 v14, v14, v71, -v102
	v_fma_f32 v15, v15, v66, -v103
	s_waitcnt lgkmcnt(15)
	v_fma_f32 v16, v16, v64, -v104
	v_fma_f32 v17, v17, v85, -v105
	v_fma_f32 v18, v18, v84, -v106
	v_fma_f32 v19, v19, v83, -v107
	v_fma_f32 v20, v20, v82, -v108
	v_fma_f32 v21, v21, v81, -v109
	v_fma_f32 v22, v22, v80, -v110
	v_fma_f32 v23, v23, v79, -v111
	v_fma_f32 v24, v24, v78, -v112
	v_fma_f32 v25, v25, v77, -v113
	v_fma_f32 v26, v26, v76, -v114
	v_fma_f32 v27, v27, v75, -v115
	v_fma_f32 v28, v28, v74, -v116
	v_fma_f32 v29, v29, v73, -v117
	v_fma_f32 v30, v30, v71, -v118
	v_fma_f32 v31, v31, v66, -v119
	s_waitcnt lgkmcnt(8)
	v_fma_f32 v32, v32, v64, -v120
	v_fma_f32 v33, v33, v85, -v121
	v_fma_f32 v34, v34, v84, -v122
	v_fma_f32 v35, v35, v83, -v123
	v_fma_f32 v36, v36, v82, -v124
	v_fma_f32 v37, v37, v81, -v125
	v_fma_f32 v38, v38, v80, -v126
	v_fma_f32 v39, v39, v79, -v127
	v_fma_f32 v40, v40, v78, -v198
	v_fma_f32 v41, v41, v77, -v199
	v_fma_f32 v42, v42, v76, -v200
	v_fma_f32 v43, v43, v75, -v201
	v_fma_f32 v44, v44, v74, -v202
	v_fma_f32 v45, v45, v73, -v203
	v_fma_f32 v46, v46, v71, -v204
	v_fma_f32 v47, v47, v66, -v205
	s_waitcnt lgkmcnt(0)
	v_fma_f32 v48, v48, v64, -v206
	v_fma_f32 v49, v49, v85, -v207
	v_fma_f32 v50, v50, v84, -v208
	v_fma_f32 v51, v51, v83, -v209
	v_fma_f32 v52, v52, v82, -v210
	v_fma_f32 v53, v53, v81, -v211
	v_fma_f32 v54, v54, v80, -v212
	v_fma_f32 v55, v55, v79, -v213
	v_fma_f32 v56, v56, v78, -v214
	v_fma_f32 v57, v57, v77, -v215
	v_fma_f32 v58, v58, v76, -v216
	v_fma_f32 v59, v59, v75, -v217
	v_fma_f32 v60, v60, v74, -v218
	v_fma_f32 v61, v61, v73, -v219
	v_fma_f32 v62, v62, v71, -v220
	v_fma_f32 v63, v63, v66, -v221
	v_mul_f32_e32 v222, v16, v16
	v_mul_f32_e32 v223, v17, v17
	v_mul_f32_e32 v224, v18, v18
	v_mul_f32_e32 v225, v19, v19
	v_mul_f32_e32 v226, v20, v20
	v_mul_f32_e32 v227, v21, v21
	v_mul_f32_e32 v228, v22, v22
	v_mul_f32_e32 v229, v23, v23
	v_mul_f32_e32 v230, v24, v24
	v_mul_f32_e32 v231, v25, v25
	v_mul_f32_e32 v232, v26, v26
	v_mul_f32_e32 v233, v27, v27
	v_mul_f32_e32 v234, v28, v28
	v_mul_f32_e32 v235, v29, v29
	v_mul_f32_e32 v236, v30, v30
	v_mul_f32_e32 v237, v31, v31
	v_fmac_f32_e32 v222, v0, v0
	v_fmac_f32_e32 v223, v1, v1
	v_fmac_f32_e32 v224, v2, v2
	v_fmac_f32_e32 v225, v3, v3
	v_fmac_f32_e32 v226, v4, v4
	v_fmac_f32_e32 v227, v5, v5
	v_fmac_f32_e32 v228, v6, v6
	v_fmac_f32_e32 v229, v7, v7
	v_fmac_f32_e32 v230, v8, v8
	v_fmac_f32_e32 v231, v9, v9
	v_fmac_f32_e32 v232, v10, v10
	v_fmac_f32_e32 v233, v11, v11
	v_fmac_f32_e32 v234, v12, v12
	v_fmac_f32_e32 v235, v13, v13
	v_fmac_f32_e32 v236, v14, v14
	v_fmac_f32_e32 v237, v15, v15
	v_fmac_f32_e32 v222, v32, v32
	v_fmac_f32_e32 v223, v33, v33
	v_fmac_f32_e32 v224, v34, v34
	v_fmac_f32_e32 v225, v35, v35
	v_fmac_f32_e32 v226, v36, v36
	v_fmac_f32_e32 v227, v37, v37
	v_fmac_f32_e32 v228, v38, v38
	v_fmac_f32_e32 v229, v39, v39
	v_fmac_f32_e32 v230, v40, v40
	v_fmac_f32_e32 v231, v41, v41
	v_fmac_f32_e32 v232, v42, v42
	v_fmac_f32_e32 v233, v43, v43
	v_fmac_f32_e32 v234, v44, v44
	v_fmac_f32_e32 v235, v45, v45
	v_fmac_f32_e32 v236, v46, v46
	v_fmac_f32_e32 v237, v47, v47
	v_fmac_f32_e32 v222, v48, v48
	v_fmac_f32_e32 v223, v49, v49
; template <bool FIXED> __device__ __forceinline__ void attn_unit(int b, int h, int qb, const bf16* __restrict__ P, bf16* __restrict__ MIX, const float* __restrict__ BT, const float* __restrict__ subg, ...
;     ...
;     for (int r = 0; r < 16; ++r) { float y[4]; float ss = 0.f;
; #pragma unroll
;       for (int d0 = 0; d0 < 4; ++d0) { y[d0] = o[d0][r] * rli[r] - xch[(d0 * 16 + r) * 64]; ss += y[d0] * y[d0]; }
;       ss += __shfl_xor(ss, 1); ss += __shfl_xor(ss, 2); ss += __shfl_xor(ss, 4); ss += __shfl_xor(ss, 8); ss += __shfl_xor(ss, 16);
	v_fmac_f32_e32 v224, v50, v50
	v_fmac_f32_e32 v225, v51, v51
	v_fmac_f32_e32 v226, v52, v52
	v_fmac_f32_e32 v227, v53, v53
	v_fmac_f32_e32 v228, v54, v54
	v_fmac_f32_e32 v229, v55, v55
	v_fmac_f32_e32 v230, v56, v56
	v_fmac_f32_e32 v231, v57, v57
	v_fmac_f32_e32 v232, v58, v58
	v_fmac_f32_e32 v233, v59, v59
	v_fmac_f32_e32 v234, v60, v60
	v_fmac_f32_e32 v235, v61, v61
	v_fmac_f32_e32 v236, v62, v62
	v_fmac_f32_e32 v237, v63, v63
	v_add_f32_dpp v238, v222, v222 quad_perm:[1,0,3,2] row_mask:0xf bank_mask:0xf
	v_add_f32_dpp v239, v223, v223 quad_perm:[1,0,3,2] row_mask:0xf bank_mask:0xf
	v_add_f32_dpp v240, v224, v224 quad_perm:[1,0,3,2] row_mask:0xf bank_mask:0xf
	v_add_f32_dpp v241, v225, v225 quad_perm:[1,0,3,2] row_mask:0xf bank_mask:0xf
	v_add_f32_dpp v242, v226, v226 quad_perm:[1,0,3,2] row_mask:0xf bank_mask:0xf
	v_add_f32_dpp v243, v227, v227 quad_perm:[1,0,3,2] row_mask:0xf bank_mask:0xf
	v_add_f32_dpp v244, v228, v228 quad_perm:[1,0,3,2] row_mask:0xf bank_mask:0xf
	v_add_f32_dpp v245, v229, v229 quad_perm:[1,0,3,2] row_mask:0xf bank_mask:0xf
	v_add_f32_dpp v246, v230, v230 quad_perm:[1,0,3,2] row_mask:0xf bank_mask:0xf
	v_add_f32_dpp v247, v231, v231 quad_perm:[1,0,3,2] row_mask:0xf bank_mask:0xf
	v_add_f32_dpp v248, v232, v232 quad_perm:[1,0,3,2] row_mask:0xf bank_mask:0xf
	v_add_f32_dpp v249, v233, v233 quad_perm:[1,0,3,2] row_mask:0xf bank_mask:0xf
	v_add_f32_dpp v250, v234, v234 quad_perm:[1,0,3,2] row_mask:0xf bank_mask:0xf
	v_add_f32_dpp v251, v235, v235 quad_perm:[1,0,3,2] row_mask:0xf bank_mask:0xf
	v_add_f32_dpp v252, v236, v236 quad_perm:[1,0,3,2] row_mask:0xf bank_mask:0xf
	v_add_f32_dpp v253, v237, v237 quad_perm:[1,0,3,2] row_mask:0xf bank_mask:0xf
	v_add_f32_dpp v222, v238, v238 quad_perm:[2,3,0,1] row_mask:0xf bank_mask:0xf
	v_add_f32_dpp v223, v239, v239 quad_perm:[2,3,0,1] row_mask:0xf bank_mask:0xf
	v_add_f32_dpp v224, v240, v240 quad_perm:[2,3,0,1] row_mask:0xf bank_mask:0xf
	v_add_f32_dpp v225, v241, v241 quad_perm:[2,3,0,1] row_mask:0xf bank_mask:0xf
	v_add_f32_dpp v226, v242, v242 quad_perm:[2,3,0,1] row_mask:0xf bank_mask:0xf
	v_add_f32_dpp v227, v243, v243 quad_perm:[2,3,0,1] row_mask:0xf bank_mask:0xf
	v_add_f32_dpp v228, v244, v244 quad_perm:[2,3,0,1] row_mask:0xf bank_mask:0xf
	v_add_f32_dpp v229, v245, v245 quad_perm:[2,3,0,1] row_mask:0xf bank_mask:0xf
	v_add_f32_dpp v230, v246, v246 quad_perm:[2,3,0,1] row_mask:0xf bank_mask:0xf
	v_add_f32_dpp v231, v247, v247 quad_perm:[2,3,0,1] row_mask:0xf bank_mask:0xf
	v_add_f32_dpp v232, v248, v248 quad_perm:[2,3,0,1] row_mask:0xf bank_mask:0xf
	v_add_f32_dpp v233, v249, v249 quad_perm:[2,3,0,1] row_mask:0xf bank_mask:0xf
	v_add_f32_dpp v234, v250, v250 quad_perm:[2,3,0,1] row_mask:0xf bank_mask:0xf
	v_add_f32_dpp v235, v251, v251 quad_perm:[2,3,0,1] row_mask:0xf bank_mask:0xf
	v_add_f32_dpp v236, v252, v252 quad_perm:[2,3,0,1] row_mask:0xf bank_mask:0xf
	v_add_f32_dpp v237, v253, v253 quad_perm:[2,3,0,1] row_mask:0xf bank_mask:0xf
	v_add_f32_dpp v238, v222, v222 row_half_mirror row_mask:0xf bank_mask:0xf
	v_add_f32_dpp v239, v223, v223 row_half_mirror row_mask:0xf bank_mask:0xf
	v_add_f32_dpp v240, v224, v224 row_half_mirror row_mask:0xf bank_mask:0xf
	v_add_f32_dpp v241, v225, v225 row_half_mirror row_mask:0xf bank_mask:0xf
	v_add_f32_dpp v242, v226, v226 row_half_mirror row_mask:0xf bank_mask:0xf
	v_add_f32_dpp v243, v227, v227 row_half_mirror row_mask:0xf bank_mask:0xf
	v_add_f32_dpp v244, v228, v228 row_half_mirror row_mask:0xf bank_mask:0xf
	v_add_f32_dpp v245, v229, v229 row_half_mirror row_mask:0xf bank_mask:0xf
	v_add_f32_dpp v246, v230, v230 row_half_mirror row_mask:0xf bank_mask:0xf
	v_add_f32_dpp v247, v231, v231 row_half_mirror row_mask:0xf bank_mask:0xf
	v_add_f32_dpp v248, v232, v232 row_half_mirror row_mask:0xf bank_mask:0xf
	v_add_f32_dpp v249, v233, v233 row_half_mirror row_mask:0xf bank_mask:0xf
	v_add_f32_dpp v250, v234, v234 row_half_mirror row_mask:0xf bank_mask:0xf
	v_add_f32_dpp v251, v235, v235 row_half_mirror row_mask:0xf bank_mask:0xf
	v_add_f32_dpp v252, v236, v236 row_half_mirror row_mask:0xf bank_mask:0xf
	v_add_f32_dpp v253, v237, v237 row_half_mirror row_mask:0xf bank_mask:0xf
	v_add_f32_dpp v222, v238, v238 row_ror:8 row_mask:0xf bank_mask:0xf
	v_add_f32_dpp v223, v239, v239 row_ror:8 row_mask:0xf bank_mask:0xf
	v_add_f32_dpp v224, v240, v240 row_ror:8 row_mask:0xf bank_mask:0xf
	v_add_f32_dpp v225, v241, v241 row_ror:8 row_mask:0xf bank_mask:0xf
	v_add_f32_dpp v226, v242, v242 row_ror:8 row_mask:0xf bank_mask:0xf
	v_add_f32_dpp v227, v243, v243 row_ror:8 row_mask:0xf bank_mask:0xf
	v_add_f32_dpp v228, v244, v244 row_ror:8 row_mask:0xf bank_mask:0xf
	v_add_f32_dpp v229, v245, v245 row_ror:8 row_mask:0xf bank_mask:0xf
	v_add_f32_dpp v230, v246, v246 row_ror:8 row_mask:0xf bank_mask:0xf
	v_add_f32_dpp v231, v247, v247 row_ror:8 row_mask:0xf bank_mask:0xf
	v_add_f32_dpp v232, v248, v248 row_ror:8 row_mask:0xf bank_mask:0xf
	v_add_f32_dpp v233, v249, v249 row_ror:8 row_mask:0xf bank_mask:0xf
	v_add_f32_dpp v234, v250, v250 row_ror:8 row_mask:0xf bank_mask:0xf
	v_add_f32_dpp v235, v251, v251 row_ror:8 row_mask:0xf bank_mask:0xf
	v_add_f32_dpp v236, v252, v252 row_ror:8 row_mask:0xf bank_mask:0xf
	v_add_f32_dpp v237, v253, v253 row_ror:8 row_mask:0xf bank_mask:0xf
	v_mov_b32_e32 v238, v222
	v_mov_b32_e32 v239, v223
	v_mov_b32_e32 v240, v224
	v_mov_b32_e32 v241, v225
	v_mov_b32_e32 v242, v226
	v_mov_b32_e32 v243, v227
	v_mov_b32_e32 v244, v228
	v_mov_b32_e32 v245, v229
	v_mov_b32_e32 v246, v230
	v_mov_b32_e32 v247, v231
	v_mov_b32_e32 v248, v232
	v_mov_b32_e32 v249, v233
	v_mov_b32_e32 v250, v234
	v_mov_b32_e32 v251, v235
	v_mov_b32_e32 v252, v236
	v_mov_b32_e32 v253, v237
	v_permlane16_swap_b32_e32 v222, v238
	v_permlane16_swap_b32_e32 v223, v239
	v_permlane16_swap_b32_e32 v224, v240
	v_permlane16_swap_b32_e32 v225, v241
	v_permlane16_swap_b32_e32 v226, v242
	v_permlane16_swap_b32_e32 v227, v243
	v_permlane16_swap_b32_e32 v228, v244
	v_permlane16_swap_b32_e32 v229, v245
	v_permlane16_swap_b32_e32 v230, v246
	v_permlane16_swap_b32_e32 v231, v247
	v_permlane16_swap_b32_e32 v232, v248
	v_permlane16_swap_b32_e32 v233, v249
	v_permlane16_swap_b32_e32 v234, v250
	v_permlane16_swap_b32_e32 v235, v251
	v_permlane16_swap_b32_e32 v236, v252
	v_permlane16_swap_b32_e32 v237, v253
	v_add_f32_e32 v222, v222, v238
	v_add_f32_e32 v223, v223, v239
	v_add_f32_e32 v224, v224, v240
	v_add_f32_e32 v225, v225, v241
	v_add_f32_e32 v226, v226, v242
	v_add_f32_e32 v227, v227, v243
	v_add_f32_e32 v228, v228, v244
	v_add_f32_e32 v229, v229, v245
	v_add_f32_e32 v230, v230, v246
	v_add_f32_e32 v231, v231, v247
	v_add_f32_e32 v232, v232, v248
	v_add_f32_e32 v233, v233, v249
	v_add_f32_e32 v234, v234, v250
	v_add_f32_e32 v235, v235, v251
	v_add_f32_e32 v236, v236, v252
	v_add_f32_e32 v237, v237, v253
	s_and_b64 vcc, exec, s[30:31]
	s_cbranch_vccz .Lmy_w0_a
	s_waitcnt vmcnt(4)
	s_branch .Lmy_w1_a
